# flag-guarded cross-chunk prefetch combined with the shortened (hoisted) helper pipeline
# baseline (speedup 1.0000x reference)
.Lmy_f_nol34:
	s_waitcnt lgkmcnt(0)
	s_bfe_u32 s96, s62, 0x20006
	s_and_b32 s97, s96, 1
	s_mul_i32 s97, s97, 0x2700
	s_mov_b32 s101, 0x1c000
	s_mov_b32 s100, 0x6100
	s_bitcmp0_b32 s65, 0
	s_cselect_b32 s101, 0xe000, s101
	s_cselect_b32 s100, 0x4e00, s100
	s_cmp_gt_u32 s96, 1
	s_cselect_b32 s100, s100, 0
	s_add_i32 s97, s97, s101
	s_add_i32 s97, s97, s100
	ds_read_b32 v80, v198
	ds_read_b32 v81, v198 offset:256
	ds_read_b32 v82, v198 offset:512
	ds_read_b32 v83, v198 offset:768
	ds_read_b32 v84, v198 offset:1024
	ds_read_b32 v85, v198 offset:1280
	ds_read_b32 v86, v198 offset:1536
	ds_read_b32 v87, v198 offset:1792
	ds_read_b32 v88, v198 offset:8192
	ds_read_b32 v89, v198 offset:8448
	ds_read_b32 v90, v198 offset:8704
	ds_read_b32 v91, v198 offset:8960
	ds_read_b32 v92, v198 offset:9216
	ds_read_b32 v93, v198 offset:9472
	ds_read_b32 v94, v198 offset:9728
	ds_read_b32 v95, v198 offset:9984
	ds_read_b32 v96, v198 offset:32768
	ds_read_b32 v97, v198 offset:33024
	ds_read_b32 v98, v198 offset:33280
	ds_read_b32 v99, v198 offset:33536
	ds_read_b32 v100, v198 offset:33792
	ds_read_b32 v101, v198 offset:34048
	ds_read_b32 v102, v198 offset:34304
	ds_read_b32 v103, v198 offset:34560
	s_add_i32 s100, s97, 0x0
	v_add_u32_e32 v76, s100, v200
	v_add_u32_e32 v77, s100, v201
	v_add_u32_e32 v78, s100, v202
	v_add_u32_e32 v79, s100, v203
	s_waitcnt lgkmcnt(15)
	v_mov_b32_e32 v104, v80
	v_mul_f32_e32 v105, v104, v81
	v_mul_f32_e32 v106, v105, v82
	v_mul_f32_e32 v107, v106, v83
	v_mul_f32_e32 v108, v107, v84
	v_mul_f32_e32 v109, v108, v85
	v_mul_f32_e32 v110, v109, v86
	v_mul_f32_e32 v111, v110, v87
	v_mov_b32_e32 v112, v88
	s_waitcnt lgkmcnt(14)
	v_mul_f32_e32 v113, v104, v89
	s_waitcnt lgkmcnt(13)
	v_mul_f32_e32 v114, v105, v90
	s_waitcnt lgkmcnt(12)
	v_mul_f32_e32 v115, v106, v91
	s_waitcnt lgkmcnt(11)
	v_mul_f32_e32 v116, v107, v92
	s_waitcnt lgkmcnt(10)
	v_mul_f32_e32 v117, v108, v93
	s_waitcnt lgkmcnt(9)
	v_mul_f32_e32 v118, v109, v94
	s_waitcnt lgkmcnt(8)
	v_mul_f32_e32 v119, v110, v95
	s_waitcnt lgkmcnt(7)
	v_mul_f32_e32 v120, v104, v96
	s_waitcnt lgkmcnt(6)
	v_mul_f32_e32 v121, v105, v97
	s_waitcnt lgkmcnt(5)
	v_mul_f32_e32 v122, v106, v98
	s_waitcnt lgkmcnt(4)
	v_mul_f32_e32 v123, v107, v99
	s_waitcnt lgkmcnt(3)
	v_mul_f32_e32 v124, v108, v100
	s_waitcnt lgkmcnt(2)
	v_mul_f32_e32 v125, v109, v101
	s_waitcnt lgkmcnt(1)
	v_mul_f32_e32 v126, v110, v102
	s_waitcnt lgkmcnt(0)
	v_mul_f32_e32 v127, v111, v103
	ds_write_b32 v76, v112
	ds_write_b32 v77, v113
	ds_write_b32 v78, v114
	ds_write_b32 v79, v115
	ds_write_b32 v76, v116 offset:64
	ds_write_b32 v77, v117 offset:64
	ds_write_b32 v78, v118 offset:64
	ds_write_b32 v79, v119 offset:64
	ds_write_b32 v76, v120 offset:128
	ds_write_b32 v77, v121 offset:128
	ds_write_b32 v78, v122 offset:128
	ds_write_b32 v79, v123 offset:128
	ds_write_b32 v76, v124 offset:192
	ds_write_b32 v77, v125 offset:192
	ds_write_b32 v78, v126 offset:192
	ds_write_b32 v79, v127 offset:192
	s_waitcnt lgkmcnt(0)
	ds_read_b32 v88, v198 offset:16384
	ds_read_b32 v89, v198 offset:16640
	ds_read_b32 v90, v198 offset:16896
	ds_read_b32 v91, v198 offset:17152
	ds_read_b32 v92, v198 offset:17408
	ds_read_b32 v93, v198 offset:17664
	ds_read_b32 v94, v198 offset:17920
	ds_read_b32 v95, v198 offset:18176
	ds_read_b32 v96, v198 offset:24576
	ds_read_b32 v97, v198 offset:24832
	ds_read_b32 v98, v198 offset:25088
	ds_read_b32 v99, v198 offset:25344
	ds_read_b32 v100, v198 offset:25600
	ds_read_b32 v101, v198 offset:25856
	ds_read_b32 v102, v198 offset:26112
	ds_read_b32 v103, v198 offset:26368
	s_add_i32 s101, s97, 0x1000
	v_add_u32_e32 v74, s101, v204
	s_add_i32 s101, s97, 0x2000
	v_add_u32_e32 v75, s101, v205
	v_rcp_f32_e32 v112, v104
	v_rcp_f32_e32 v113, v105
	v_rcp_f32_e32 v114, v106
	v_rcp_f32_e32 v115, v107
	v_rcp_f32_e32 v116, v108
	v_rcp_f32_e32 v117, v109
	v_rcp_f32_e32 v118, v110
	v_rcp_f32_e32 v119, v111
	s_waitcnt lgkmcnt(7)
	v_mul_f32_e32 v120, v112, v96
	s_waitcnt lgkmcnt(6)
	v_mul_f32_e32 v121, v113, v97
	s_waitcnt lgkmcnt(5)
	v_mul_f32_e32 v122, v114, v98
	s_waitcnt lgkmcnt(4)
	v_mul_f32_e32 v123, v115, v99
	s_waitcnt lgkmcnt(3)
	v_mul_f32_e32 v124, v116, v100
	s_waitcnt lgkmcnt(2)
	v_mul_f32_e32 v125, v117, v101
	s_waitcnt lgkmcnt(1)
	v_mul_f32_e32 v126, v118, v102
	s_waitcnt lgkmcnt(0)
	v_mul_f32_e32 v127, v119, v103
	v_mul_f32_e32 v112, v112, v88
	v_mul_f32_e32 v113, v113, v89
	v_mul_f32_e32 v114, v114, v90
	v_mul_f32_e32 v115, v115, v91
	v_mul_f32_e32 v116, v116, v92
	v_mul_f32_e32 v117, v117, v93
	v_mul_f32_e32 v118, v118, v94
	v_mul_f32_e32 v119, v119, v95
	ds_write_b128 v74, v[112:115]
	ds_write_b128 v74, v[116:119] offset:256
	ds_write_b128 v74, v[120:123] offset:512
	ds_write_b128 v74, v[124:127] offset:768
	ds_write_b32 v75, v111
	s_waitcnt lgkmcnt(0)
	s_bfe_u32 s96, s62, 0x20006
	s_and_b32 s97, s96, 1
	s_mul_i32 s97, s97, 0x2700
	s_mov_b32 s101, 0x1c000
	s_mov_b32 s100, 0x6100
	s_bitcmp0_b32 s65, 0
	s_cselect_b32 s101, 0xe000, s101
	s_cselect_b32 s100, 0x4e00, s100
	s_cmp_gt_u32 s96, 1
	s_cselect_b32 s100, s100, 0
	s_add_i32 s97, s97, s101
	s_add_i32 s97, s97, s100
	s_mov_b32 s96, s97
	s_add_i32 s101, s96, 0x1000
	v_add_u32_e32 v78, s101, v206
	v_add_u32_e32 v79, s96, v207
	ds_read_b128 v[96:99], v79
	ds_read_b128 v[100:103], v79 offset:1024
	ds_read_b128 v[104:107], v79 offset:2048
	ds_read_b128 v[108:111], v79 offset:3072
	ds_read_b32 v80, v78
	ds_read_b32 v81, v78 offset:16
	ds_read_b32 v82, v78 offset:32
	ds_read_b32 v83, v78 offset:48
	ds_read_b32 v84, v78 offset:1024
	ds_read_b32 v85, v78 offset:1040
	ds_read_b32 v86, v78 offset:1056
	ds_read_b32 v87, v78 offset:1072
	ds_read_b32 v88, v78 offset:2048
	ds_read_b32 v89, v78 offset:2064
	ds_read_b32 v90, v78 offset:2080
	ds_read_b32 v91, v78 offset:2096
	ds_read_b32 v92, v78 offset:3072
	ds_read_b32 v93, v78 offset:3088
	ds_read_b32 v94, v78 offset:3104
	ds_read_b32 v95, v78 offset:3120
	v_add_u32_e32 v74, s96, v205
	ds_write_b32 v74, v235 offset:9728
	s_waitcnt lgkmcnt(15)
	v_mfma_f32_16x16x4_f32 v[244:247], v80, v96, 0
	v_mfma_f32_16x16x4_f32 v[240:243], v81, v97, 0
	s_waitcnt lgkmcnt(14)
	v_mfma_f32_16x16x4_f32 v[244:247], v82, v98, v[244:247]
	s_waitcnt lgkmcnt(13)
	v_mfma_f32_16x16x4_f32 v[240:243], v83, v99, v[240:243]
	s_waitcnt lgkmcnt(12)
	v_mfma_f32_16x16x4_f32 v[244:247], v84, v100, v[244:247]
	s_waitcnt lgkmcnt(11)
	v_mfma_f32_16x16x4_f32 v[240:243], v85, v101, v[240:243]
	s_waitcnt lgkmcnt(10)
	v_mfma_f32_16x16x4_f32 v[244:247], v86, v102, v[244:247]
	s_waitcnt lgkmcnt(9)
	v_mfma_f32_16x16x4_f32 v[240:243], v87, v103, v[240:243]
	s_waitcnt lgkmcnt(8)
	v_mfma_f32_16x16x4_f32 v[244:247], v88, v104, v[244:247]
	s_waitcnt lgkmcnt(7)
	v_mfma_f32_16x16x4_f32 v[240:243], v89, v105, v[240:243]
	s_waitcnt lgkmcnt(6)
	v_mfma_f32_16x16x4_f32 v[244:247], v90, v106, v[244:247]
	s_waitcnt lgkmcnt(5)
	v_mfma_f32_16x16x4_f32 v[240:243], v91, v107, v[240:243]
	s_waitcnt lgkmcnt(4)
	v_mfma_f32_16x16x4_f32 v[244:247], v92, v108, v[244:247]
	s_waitcnt lgkmcnt(3)
	v_mfma_f32_16x16x4_f32 v[240:243], v93, v109, v[240:243]
	s_waitcnt lgkmcnt(2)
	v_mfma_f32_16x16x4_f32 v[244:247], v94, v110, v[244:247]
	s_waitcnt lgkmcnt(1)
	v_mfma_f32_16x16x4_f32 v[240:243], v95, v111, v[240:243]
	s_nop 9
	v_add_f32_e32 v244, v244, v240
	v_add_f32_e32 v245, v245, v241
	v_add_f32_e32 v246, v246, v242
	v_add_f32_e32 v247, v247, v243
	v_mul_f32_e32 v128, v244, v208
	v_mul_f32_e32 v129, v245, v209
	v_mul_f32_e32 v130, v246, v210
	v_mul_f32_e32 v131, v247, v211
	ds_write_b128 v79, v[128:131] offset:8448
	v_add_u32_e32 v75, s96, v216
	v_mul_f32_e32 v132, v244, v212
	v_mul_f32_e32 v133, v245, v213
	v_mul_f32_e32 v134, v246, v214
	v_mul_f32_e32 v135, v247, v215
	s_mov_b64 exec, 0x00ff00ff
	ds_write_b32 v75, v132 offset:9472
	ds_write_b32 v75, v133 offset:9504
	ds_write_b32 v75, v134 offset:9536
	ds_write_b32 v75, v135 offset:9568
	s_mov_b64 exec, -1
	s_cmpk_eq_u32 s62, 0x100
	s_cbranch_scc0 .Lmy_f_noflag
	v_mov_b32_e32 v72, 0x22040
	v_mov_b32_e32 v73, s22
	ds_write_b32 v72, v73
.Lmy_f_noflag:
	s_setprio 0
	s_branch .LBB0_655
	s_nop 0
	s_nop 0
	s_nop 0
	s_nop 0
	s_nop 0
	s_nop 0
	s_nop 0
	s_nop 0
	s_nop 0
	s_nop 0
	s_nop 0
	s_nop 0
	s_nop 0
	s_nop 0
	s_nop 0
